# baseline (speedup 1.0000x reference)
; __device__ __forceinline__ float bflo(unsigned v) { return __uint_as_float(v << 16); }
; __device__ __forceinline__ float bfhi(unsigned v) { return __uint_as_float(v & 0xffff0000u); }
; __device__ __forceinline__ void phase4(const Params& p, char* shm) {
;     ...
;       if (half == 0) {
; #pragma unroll
;     for (int ai = 0; ai < 2; ++ai) {
;       GEMM_IDS;
;       char* const cfb = CF_BASE(shm);
;       const u16* gsrc = Gates + (brow + ai * 128) * 4096 + bcol;
; #pragma unroll
;       for (int b8 = 0; b8 < 2; ++b8) {
;         u32x2 ga[8], gb[8];
; #pragma unroll
;         for (int i = 0; i < 8; ++i) { const int id = tid + (b8 * 8 + i) * NTHR, row = id >> 6, c = id & 63;
;           ga[i] = *reinterpret_cast<const u32x2*>(gsrc + (size_t)row * 4096 + c * 4);
;           gb[i] = *reinterpret_cast<const u32x2*>(gsrc + (size_t)row * 4096 + 2048 + c * 4); }
; #pragma unroll
;         for (int i = 0; i < 8; ++i) { const int id = tid + (b8 * 8 + i) * NTHR, row = id >> 6, c = id & 63;
;           f32x4 rt = { bflo(ga[i][0]) * __builtin_amdgcn_rcpf(bflo(gb[i][0])), bfhi(ga[i][0]) * __builtin_amdgcn_rcpf(bfhi(gb[i][0])),
;                        bflo(ga[i][1]) * __builtin_amdgcn_rcpf(bflo(gb[i][1])), bfhi(ga[i][1]) * __builtin_amdgcn_rcpf(bfhi(gb[i][1])) };
;           *reinterpret_cast<f32x4*>(shm + (row * CF_LD + c * 4) * 4) = rt; }
;       }
;       __syncthreads();
.LBB0_457:
	s_or_b64 exec, exec, s[30:31]
	s_andn2_b64 vcc, exec, s[20:21]
	s_barrier
	s_cbranch_vccnz .LBB0_450
	v_mov_b32_e32 v187, v1
	v_lshlrev_b32_e32 v134, 4, v1
	v_add_u32_e32 v135, 0x100000, v134
	v_lshrrev_b32_e32 v184, 5, v1
	v_mul_u32_u24_e32 v184, 0x410, v184
	v_and_b32_e32 v185, 31, v1
	v_lshl_add_u32 v184, v185, 5, v184
	v_add_u32_e32 v185, 0x10400, v184
	v_and_b32_e32 v252, 15, v1
	v_lshrrev_b32_e32 v253, 8, v1
	v_lshl_add_u32 v252, v253, 6, v252
	v_mul_u32_u24_e32 v252, 0x410, v252
	v_bfe_u32 v253, v1, 6, 2
	v_lshl_add_u32 v252, v253, 7, v252
	v_bfe_u32 v253, v1, 4, 2
	v_lshl_add_u32 v252, v253, 4, v252
	s_mov_b64 s[98:99], s[12:13]
	global_load_dwordx4 v[188:191], v134, s[98:99]
	global_load_dwordx4 v[192:195], v135, s[98:99]
	s_add_u32 s98, s12, 0x2000
	s_addc_u32 s99, s13, 0
	global_load_dwordx4 v[196:199], v134, s[98:99]
	global_load_dwordx4 v[200:203], v135, s[98:99]
	s_add_u32 s98, s12, 0x4000
	s_addc_u32 s99, s13, 0
	global_load_dwordx4 v[204:207], v134, s[98:99]
	global_load_dwordx4 v[208:211], v135, s[98:99]
	s_add_u32 s98, s12, 0x6000
	s_addc_u32 s99, s13, 0
	global_load_dwordx4 v[212:215], v134, s[98:99]
	global_load_dwordx4 v[216:219], v135, s[98:99]
	s_add_u32 s98, s12, 0x8000
	s_addc_u32 s99, s13, 0
	global_load_dwordx4 v[220:223], v134, s[98:99]
	global_load_dwordx4 v[224:227], v135, s[98:99]
	s_add_u32 s98, s12, 0xa000
	s_addc_u32 s99, s13, 0
	global_load_dwordx4 v[228:231], v134, s[98:99]
	global_load_dwordx4 v[232:235], v135, s[98:99]
	s_add_u32 s98, s12, 0xc000
	s_addc_u32 s99, s13, 0
	global_load_dwordx4 v[236:239], v134, s[98:99]
	global_load_dwordx4 v[240:243], v135, s[98:99]
	s_add_u32 s98, s12, 0xe000
	s_addc_u32 s99, s13, 0
	global_load_dwordx4 v[244:247], v134, s[98:99]
	global_load_dwordx4 v[248:251], v135, s[98:99]
	s_mov_b64 s[98:99], s[14:15]
	global_load_dwordx4 v[136:139], v134, s[98:99]
	global_load_dwordx4 v[140:143], v135, s[98:99]
	s_add_u32 s98, s14, 0x2000
	s_addc_u32 s99, s15, 0
	global_load_dwordx4 v[144:147], v134, s[98:99]
	global_load_dwordx4 v[148:151], v135, s[98:99]
	s_add_u32 s98, s14, 0x4000
	s_addc_u32 s99, s15, 0
	global_load_dwordx4 v[152:155], v134, s[98:99]
	global_load_dwordx4 v[156:159], v135, s[98:99]
	s_add_u32 s98, s14, 0x6000
	s_addc_u32 s99, s15, 0
	global_load_dwordx4 v[160:163], v134, s[98:99]
	global_load_dwordx4 v[164:167], v135, s[98:99]
	s_waitcnt vmcnt(22)
	v_lshlrev_b32_e32 v176, 16, v192
	v_and_b32_e32 v177, 0xffff0000, v192
	v_lshlrev_b32_e32 v178, 16, v193
	v_and_b32_e32 v179, 0xffff0000, v193
	v_lshlrev_b32_e32 v180, 16, v194
	v_and_b32_e32 v181, 0xffff0000, v194
	v_lshlrev_b32_e32 v182, 16, v195
	v_and_b32_e32 v183, 0xffff0000, v195
	v_rcp_f32_e32 v176, v176
	v_rcp_f32_e32 v177, v177
	v_rcp_f32_e32 v178, v178
	v_rcp_f32_e32 v179, v179
	v_rcp_f32_e32 v180, v180
	v_rcp_f32_e32 v181, v181
	v_rcp_f32_e32 v182, v182
	v_rcp_f32_e32 v183, v183
	v_lshlrev_b32_e32 v168, 16, v188
	v_and_b32_e32 v169, 0xffff0000, v188
	v_lshlrev_b32_e32 v170, 16, v189
	v_and_b32_e32 v171, 0xffff0000, v189
	v_lshlrev_b32_e32 v172, 16, v190
	v_and_b32_e32 v173, 0xffff0000, v190
	v_lshlrev_b32_e32 v174, 16, v191
	v_and_b32_e32 v175, 0xffff0000, v191
	v_pk_mul_f32 v[168:169], v[168:169], v[176:177]
	v_pk_mul_f32 v[170:171], v[170:171], v[178:179]
	v_pk_mul_f32 v[172:173], v[172:173], v[180:181]
	v_pk_mul_f32 v[174:175], v[174:175], v[182:183]
	ds_write_b128 v184, v[168:171]
	ds_write_b128 v184, v[172:175] offset:16
	s_waitcnt vmcnt(20)
	v_lshlrev_b32_e32 v176, 16, v200
	v_and_b32_e32 v177, 0xffff0000, v200
	v_lshlrev_b32_e32 v178, 16, v201
	v_and_b32_e32 v179, 0xffff0000, v201
	v_lshlrev_b32_e32 v180, 16, v202
	v_and_b32_e32 v181, 0xffff0000, v202
	v_lshlrev_b32_e32 v182, 16, v203
	v_and_b32_e32 v183, 0xffff0000, v203
	v_rcp_f32_e32 v176, v176
	v_rcp_f32_e32 v177, v177
	v_rcp_f32_e32 v178, v178
	v_rcp_f32_e32 v179, v179
	v_rcp_f32_e32 v180, v180
	v_rcp_f32_e32 v181, v181
	v_rcp_f32_e32 v182, v182
	v_rcp_f32_e32 v183, v183
	v_lshlrev_b32_e32 v168, 16, v196
	v_and_b32_e32 v169, 0xffff0000, v196
	v_lshlrev_b32_e32 v170, 16, v197
	v_and_b32_e32 v171, 0xffff0000, v197
	v_lshlrev_b32_e32 v172, 16, v198
	v_and_b32_e32 v173, 0xffff0000, v198
	v_lshlrev_b32_e32 v174, 16, v199
	v_and_b32_e32 v175, 0xffff0000, v199
	v_pk_mul_f32 v[168:169], v[168:169], v[176:177]
	v_pk_mul_f32 v[170:171], v[170:171], v[178:179]
	v_pk_mul_f32 v[172:173], v[172:173], v[180:181]
	v_pk_mul_f32 v[174:175], v[174:175], v[182:183]
	ds_write_b128 v184, v[168:171] offset:16640
	ds_write_b128 v184, v[172:175] offset:16656
	s_waitcnt vmcnt(18)
	v_lshlrev_b32_e32 v176, 16, v208
	v_and_b32_e32 v177, 0xffff0000, v208
	v_lshlrev_b32_e32 v178, 16, v209
	v_and_b32_e32 v179, 0xffff0000, v209
	v_lshlrev_b32_e32 v180, 16, v210
	v_and_b32_e32 v181, 0xffff0000, v210
	v_lshlrev_b32_e32 v182, 16, v211
	v_and_b32_e32 v183, 0xffff0000, v211
	v_rcp_f32_e32 v176, v176
	v_rcp_f32_e32 v177, v177
	v_rcp_f32_e32 v178, v178
	v_rcp_f32_e32 v179, v179
	v_rcp_f32_e32 v180, v180
	v_rcp_f32_e32 v181, v181
	v_rcp_f32_e32 v182, v182
	v_rcp_f32_e32 v183, v183
	v_lshlrev_b32_e32 v168, 16, v204
	v_and_b32_e32 v169, 0xffff0000, v204
	v_lshlrev_b32_e32 v170, 16, v205
	v_and_b32_e32 v171, 0xffff0000, v205
	v_lshlrev_b32_e32 v172, 16, v206
	v_and_b32_e32 v173, 0xffff0000, v206
	v_lshlrev_b32_e32 v174, 16, v207
	v_and_b32_e32 v175, 0xffff0000, v207
	v_pk_mul_f32 v[168:169], v[168:169], v[176:177]
	v_pk_mul_f32 v[170:171], v[170:171], v[178:179]
	v_pk_mul_f32 v[172:173], v[172:173], v[180:181]
	v_pk_mul_f32 v[174:175], v[174:175], v[182:183]
	ds_write_b128 v184, v[168:171] offset:33280
	ds_write_b128 v184, v[172:175] offset:33296
	s_waitcnt vmcnt(16)
; __device__ __forceinline__ float bflo(unsigned v) { return __uint_as_float(v << 16); }
; __device__ __forceinline__ float bfhi(unsigned v) { return __uint_as_float(v & 0xffff0000u); }
; __device__ __forceinline__ void phase4(const Params& p, char* shm) {
;     ...
;         for (int i = 0; i < 8; ++i) { const int id = tid + (b8 * 8 + i) * NTHR, row = id >> 6, c = id & 63;
;           ga[i] = *reinterpret_cast<const u32x2*>(gsrc + (size_t)row * 4096 + c * 4);
;           gb[i] = *reinterpret_cast<const u32x2*>(gsrc + (size_t)row * 4096 + 2048 + c * 4); }
; #pragma unroll
;         for (int i = 0; i < 8; ++i) { const int id = tid + (b8 * 8 + i) * NTHR, row = id >> 6, c = id & 63;
;           f32x4 rt = { bflo(ga[i][0]) * __builtin_amdgcn_rcpf(bflo(gb[i][0])), bfhi(ga[i][0]) * __builtin_amdgcn_rcpf(bfhi(gb[i][0])),
;                        bflo(ga[i][1]) * __builtin_amdgcn_rcpf(bflo(gb[i][1])), bfhi(ga[i][1]) * __builtin_amdgcn_rcpf(bfhi(gb[i][1])) };
;           *reinterpret_cast<f32x4*>(shm + (row * CF_LD + c * 4) * 4) = rt; }
	v_lshlrev_b32_e32 v176, 16, v216
	v_and_b32_e32 v177, 0xffff0000, v216
	v_lshlrev_b32_e32 v178, 16, v217
	v_and_b32_e32 v179, 0xffff0000, v217
	v_lshlrev_b32_e32 v180, 16, v218
	v_and_b32_e32 v181, 0xffff0000, v218
	v_lshlrev_b32_e32 v182, 16, v219
	v_and_b32_e32 v183, 0xffff0000, v219
	v_rcp_f32_e32 v176, v176
	v_rcp_f32_e32 v177, v177
	v_rcp_f32_e32 v178, v178
	v_rcp_f32_e32 v179, v179
	v_rcp_f32_e32 v180, v180
	v_rcp_f32_e32 v181, v181
	v_rcp_f32_e32 v182, v182
	v_rcp_f32_e32 v183, v183
	v_lshlrev_b32_e32 v168, 16, v212
	v_and_b32_e32 v169, 0xffff0000, v212
	v_lshlrev_b32_e32 v170, 16, v213
	v_and_b32_e32 v171, 0xffff0000, v213
	v_lshlrev_b32_e32 v172, 16, v214
	v_and_b32_e32 v173, 0xffff0000, v214
	v_lshlrev_b32_e32 v174, 16, v215
	v_and_b32_e32 v175, 0xffff0000, v215
	v_pk_mul_f32 v[168:169], v[168:169], v[176:177]
	v_pk_mul_f32 v[170:171], v[170:171], v[178:179]
	v_pk_mul_f32 v[172:173], v[172:173], v[180:181]
	v_pk_mul_f32 v[174:175], v[174:175], v[182:183]
	ds_write_b128 v184, v[168:171] offset:49920
	ds_write_b128 v184, v[172:175] offset:49936
	s_waitcnt vmcnt(14)
	v_lshlrev_b32_e32 v176, 16, v224
	v_and_b32_e32 v177, 0xffff0000, v224
	v_lshlrev_b32_e32 v178, 16, v225
	v_and_b32_e32 v179, 0xffff0000, v225
	v_lshlrev_b32_e32 v180, 16, v226
	v_and_b32_e32 v181, 0xffff0000, v226
	v_lshlrev_b32_e32 v182, 16, v227
	v_and_b32_e32 v183, 0xffff0000, v227
	v_rcp_f32_e32 v176, v176
	v_rcp_f32_e32 v177, v177
	v_rcp_f32_e32 v178, v178
	v_rcp_f32_e32 v179, v179
	v_rcp_f32_e32 v180, v180
	v_rcp_f32_e32 v181, v181
	v_rcp_f32_e32 v182, v182
	v_rcp_f32_e32 v183, v183
	v_lshlrev_b32_e32 v168, 16, v220
	v_and_b32_e32 v169, 0xffff0000, v220
	v_lshlrev_b32_e32 v170, 16, v221
	v_and_b32_e32 v171, 0xffff0000, v221
	v_lshlrev_b32_e32 v172, 16, v222
	v_and_b32_e32 v173, 0xffff0000, v222
	v_lshlrev_b32_e32 v174, 16, v223
	v_and_b32_e32 v175, 0xffff0000, v223
	v_pk_mul_f32 v[168:169], v[168:169], v[176:177]
	v_pk_mul_f32 v[170:171], v[170:171], v[178:179]
	v_pk_mul_f32 v[172:173], v[172:173], v[180:181]
	v_pk_mul_f32 v[174:175], v[174:175], v[182:183]
	ds_write_b128 v185, v[168:171]
	ds_write_b128 v185, v[172:175] offset:16
	s_waitcnt vmcnt(12)
	v_lshlrev_b32_e32 v176, 16, v232
	v_and_b32_e32 v177, 0xffff0000, v232
	v_lshlrev_b32_e32 v178, 16, v233
	v_and_b32_e32 v179, 0xffff0000, v233
	v_lshlrev_b32_e32 v180, 16, v234
	v_and_b32_e32 v181, 0xffff0000, v234
	v_lshlrev_b32_e32 v182, 16, v235
	v_and_b32_e32 v183, 0xffff0000, v235
	v_rcp_f32_e32 v176, v176
	v_rcp_f32_e32 v177, v177
	v_rcp_f32_e32 v178, v178
	v_rcp_f32_e32 v179, v179
	v_rcp_f32_e32 v180, v180
	v_rcp_f32_e32 v181, v181
	v_rcp_f32_e32 v182, v182
	v_rcp_f32_e32 v183, v183
	v_lshlrev_b32_e32 v168, 16, v228
	v_and_b32_e32 v169, 0xffff0000, v228
	v_lshlrev_b32_e32 v170, 16, v229
	v_and_b32_e32 v171, 0xffff0000, v229
	v_lshlrev_b32_e32 v172, 16, v230
	v_and_b32_e32 v173, 0xffff0000, v230
	v_lshlrev_b32_e32 v174, 16, v231
	v_and_b32_e32 v175, 0xffff0000, v231
	v_pk_mul_f32 v[168:169], v[168:169], v[176:177]
	v_pk_mul_f32 v[170:171], v[170:171], v[178:179]
	v_pk_mul_f32 v[172:173], v[172:173], v[180:181]
	v_pk_mul_f32 v[174:175], v[174:175], v[182:183]
	ds_write_b128 v185, v[168:171] offset:16640
	ds_write_b128 v185, v[172:175] offset:16656
	s_waitcnt vmcnt(10)
	v_lshlrev_b32_e32 v176, 16, v240
	v_and_b32_e32 v177, 0xffff0000, v240
	v_lshlrev_b32_e32 v178, 16, v241
	v_and_b32_e32 v179, 0xffff0000, v241
	v_lshlrev_b32_e32 v180, 16, v242
	v_and_b32_e32 v181, 0xffff0000, v242
	v_lshlrev_b32_e32 v182, 16, v243
	v_and_b32_e32 v183, 0xffff0000, v243
	v_rcp_f32_e32 v176, v176
	v_rcp_f32_e32 v177, v177
	v_rcp_f32_e32 v178, v178
	v_rcp_f32_e32 v179, v179
	v_rcp_f32_e32 v180, v180
	v_rcp_f32_e32 v181, v181
	v_rcp_f32_e32 v182, v182
	v_rcp_f32_e32 v183, v183
	v_lshlrev_b32_e32 v168, 16, v236
	v_and_b32_e32 v169, 0xffff0000, v236
	v_lshlrev_b32_e32 v170, 16, v237
	v_and_b32_e32 v171, 0xffff0000, v237
	v_lshlrev_b32_e32 v172, 16, v238
	v_and_b32_e32 v173, 0xffff0000, v238
	v_lshlrev_b32_e32 v174, 16, v239
	v_and_b32_e32 v175, 0xffff0000, v239
	v_pk_mul_f32 v[168:169], v[168:169], v[176:177]
	v_pk_mul_f32 v[170:171], v[170:171], v[178:179]
	v_pk_mul_f32 v[172:173], v[172:173], v[180:181]
	v_pk_mul_f32 v[174:175], v[174:175], v[182:183]
	ds_write_b128 v185, v[168:171] offset:33280
	ds_write_b128 v185, v[172:175] offset:33296
	s_waitcnt vmcnt(8)
	v_lshlrev_b32_e32 v176, 16, v248
	v_and_b32_e32 v177, 0xffff0000, v248
	v_lshlrev_b32_e32 v178, 16, v249
	v_and_b32_e32 v179, 0xffff0000, v249
	v_lshlrev_b32_e32 v180, 16, v250
	v_and_b32_e32 v181, 0xffff0000, v250
	v_lshlrev_b32_e32 v182, 16, v251
	v_and_b32_e32 v183, 0xffff0000, v251
	v_rcp_f32_e32 v176, v176
	v_rcp_f32_e32 v177, v177
	v_rcp_f32_e32 v178, v178
	v_rcp_f32_e32 v179, v179
	v_rcp_f32_e32 v180, v180
	v_rcp_f32_e32 v181, v181
	v_rcp_f32_e32 v182, v182
	v_rcp_f32_e32 v183, v183
	v_lshlrev_b32_e32 v168, 16, v244
	v_and_b32_e32 v169, 0xffff0000, v244
	v_lshlrev_b32_e32 v170, 16, v245
	v_and_b32_e32 v171, 0xffff0000, v245
	v_lshlrev_b32_e32 v172, 16, v246
	v_and_b32_e32 v173, 0xffff0000, v246
	v_lshlrev_b32_e32 v174, 16, v247
	v_and_b32_e32 v175, 0xffff0000, v247
	v_pk_mul_f32 v[168:169], v[168:169], v[176:177]
	v_pk_mul_f32 v[170:171], v[170:171], v[178:179]
	v_pk_mul_f32 v[172:173], v[172:173], v[180:181]
	v_pk_mul_f32 v[174:175], v[174:175], v[182:183]
	ds_write_b128 v185, v[168:171] offset:49920
	ds_write_b128 v185, v[172:175] offset:49936
	s_waitcnt lgkmcnt(0)
	s_barrier
; __device__ __forceinline__ float bflo(unsigned v) { return __uint_as_float(v << 16); }
; __device__ __forceinline__ float bfhi(unsigned v) { return __uint_as_float(v & 0xffff0000u); }
; __device__ __forceinline__ void phase4(const Params& p, char* shm) {
;     ...
;         for (int i = 0; i < 8; ++i) { const int id = tid + (b8 * 8 + i) * NTHR, row = id >> 6, c = id & 63;
;           ga[i] = *reinterpret_cast<const u32x2*>(gsrc + (size_t)row * 4096 + c * 4);
;           gb[i] = *reinterpret_cast<const u32x2*>(gsrc + (size_t)row * 4096 + 2048 + c * 4); }
; #pragma unroll
;         for (int i = 0; i < 8; ++i) { const int id = tid + (b8 * 8 + i) * NTHR, row = id >> 6, c = id & 63;
;           f32x4 rt = { bflo(ga[i][0]) * __builtin_amdgcn_rcpf(bflo(gb[i][0])), bfhi(ga[i][0]) * __builtin_amdgcn_rcpf(bfhi(gb[i][0])),
;                        bflo(ga[i][1]) * __builtin_amdgcn_rcpf(bflo(gb[i][1])), bfhi(ga[i][1]) * __builtin_amdgcn_rcpf(bfhi(gb[i][1])) };
;           *reinterpret_cast<f32x4*>(shm + (row * CF_LD + c * 4) * 4) = rt; }
;     ...
; #pragma unroll
;       for (int bj = 0; bj < 2; ++bj)
; #pragma unroll
;         for (int m = 0; m < 4; ++m)
; #pragma unroll
;           for (int n = 0; n < 2; ++n) acc[ai][bj][m][n] *= *(const f32x4*)(cfb + CF_OFF(bj, m, n));
;       __syncthreads();
	ds_read_b128 v[168:171], v252
	ds_read_b128 v[172:175], v252 offset:64
	ds_read_b128 v[176:179], v252 offset:512
	ds_read_b128 v[180:183], v252 offset:576
	s_waitcnt lgkmcnt(3)
	v_pk_mul_f32 v[130:131], v[130:131], v[168:169]
	v_pk_mul_f32 v[132:133], v[132:133], v[170:171]
	s_waitcnt lgkmcnt(2)
	v_pk_mul_f32 v[126:127], v[126:127], v[172:173]
	v_pk_mul_f32 v[128:129], v[128:129], v[174:175]
	s_waitcnt lgkmcnt(1)
	v_pk_mul_f32 v[98:99], v[98:99], v[176:177]
	v_pk_mul_f32 v[100:101], v[100:101], v[178:179]
	s_waitcnt lgkmcnt(0)
	v_pk_mul_f32 v[94:95], v[94:95], v[180:181]
	v_pk_mul_f32 v[96:97], v[96:97], v[182:183]
	ds_read_b128 v[168:171], v252 offset:16640
	ds_read_b128 v[172:175], v252 offset:16704
	ds_read_b128 v[176:179], v252 offset:17152
	ds_read_b128 v[180:183], v252 offset:17216
	s_waitcnt lgkmcnt(3)
	v_pk_mul_f32 v[122:123], v[122:123], v[168:169]
	v_pk_mul_f32 v[124:125], v[124:125], v[170:171]
	s_waitcnt lgkmcnt(2)
	v_pk_mul_f32 v[118:119], v[118:119], v[172:173]
	v_pk_mul_f32 v[120:121], v[120:121], v[174:175]
	s_waitcnt lgkmcnt(1)
	v_pk_mul_f32 v[90:91], v[90:91], v[176:177]
	v_pk_mul_f32 v[92:93], v[92:93], v[178:179]
	s_waitcnt lgkmcnt(0)
	v_pk_mul_f32 v[86:87], v[86:87], v[180:181]
	v_pk_mul_f32 v[88:89], v[88:89], v[182:183]
	ds_read_b128 v[168:171], v252 offset:33280
	ds_read_b128 v[172:175], v252 offset:33344
	ds_read_b128 v[176:179], v252 offset:33792
	ds_read_b128 v[180:183], v252 offset:33856
	s_waitcnt lgkmcnt(3)
	v_pk_mul_f32 v[114:115], v[114:115], v[168:169]
	v_pk_mul_f32 v[116:117], v[116:117], v[170:171]
	s_waitcnt lgkmcnt(2)
	v_pk_mul_f32 v[110:111], v[110:111], v[172:173]
	v_pk_mul_f32 v[112:113], v[112:113], v[174:175]
	s_waitcnt lgkmcnt(1)
	v_pk_mul_f32 v[82:83], v[82:83], v[176:177]
	v_pk_mul_f32 v[84:85], v[84:85], v[178:179]
	s_waitcnt lgkmcnt(0)
	v_pk_mul_f32 v[78:79], v[78:79], v[180:181]
	v_pk_mul_f32 v[80:81], v[80:81], v[182:183]
	ds_read_b128 v[168:171], v252 offset:49920
	ds_read_b128 v[172:175], v252 offset:49984
	ds_read_b128 v[176:179], v252 offset:50432
	ds_read_b128 v[180:183], v252 offset:50496
	s_waitcnt lgkmcnt(3)
	v_pk_mul_f32 v[106:107], v[106:107], v[168:169]
	v_pk_mul_f32 v[108:109], v[108:109], v[170:171]
	s_waitcnt lgkmcnt(2)
	v_pk_mul_f32 v[102:103], v[102:103], v[172:173]
	v_pk_mul_f32 v[104:105], v[104:105], v[174:175]
	s_waitcnt lgkmcnt(1)
	v_pk_mul_f32 v[74:75], v[74:75], v[176:177]
	v_pk_mul_f32 v[76:77], v[76:77], v[178:179]
	s_waitcnt lgkmcnt(0)
	v_pk_mul_f32 v[70:71], v[70:71], v[180:181]
	v_pk_mul_f32 v[72:73], v[72:73], v[182:183]
	s_barrier
	s_add_u32 s98, s14, 0x8000
	s_addc_u32 s99, s15, 0
	global_load_dwordx4 v[188:191], v134, s[98:99]
	global_load_dwordx4 v[192:195], v135, s[98:99]
	s_add_u32 s98, s14, 0xa000
	s_addc_u32 s99, s15, 0
	global_load_dwordx4 v[196:199], v134, s[98:99]
	global_load_dwordx4 v[200:203], v135, s[98:99]
	s_add_u32 s98, s14, 0xc000
	s_addc_u32 s99, s15, 0
	global_load_dwordx4 v[204:207], v134, s[98:99]
	global_load_dwordx4 v[208:211], v135, s[98:99]
	s_add_u32 s98, s14, 0xe000
	s_addc_u32 s99, s15, 0
	global_load_dwordx4 v[212:215], v134, s[98:99]
	global_load_dwordx4 v[216:219], v135, s[98:99]
	s_waitcnt vmcnt(14)
	v_lshlrev_b32_e32 v176, 16, v140
	v_and_b32_e32 v177, 0xffff0000, v140
	v_lshlrev_b32_e32 v178, 16, v141
	v_and_b32_e32 v179, 0xffff0000, v141
	v_lshlrev_b32_e32 v180, 16, v142
	v_and_b32_e32 v181, 0xffff0000, v142
	v_lshlrev_b32_e32 v182, 16, v143
	v_and_b32_e32 v183, 0xffff0000, v143
	v_rcp_f32_e32 v176, v176
	v_rcp_f32_e32 v177, v177
	v_rcp_f32_e32 v178, v178
	v_rcp_f32_e32 v179, v179
	v_rcp_f32_e32 v180, v180
	v_rcp_f32_e32 v181, v181
	v_rcp_f32_e32 v182, v182
	v_rcp_f32_e32 v183, v183
	v_lshlrev_b32_e32 v168, 16, v136
	v_and_b32_e32 v169, 0xffff0000, v136
	v_lshlrev_b32_e32 v170, 16, v137
	v_and_b32_e32 v171, 0xffff0000, v137
	v_lshlrev_b32_e32 v172, 16, v138
	v_and_b32_e32 v173, 0xffff0000, v138
	v_lshlrev_b32_e32 v174, 16, v139
	v_and_b32_e32 v175, 0xffff0000, v139
	v_pk_mul_f32 v[168:169], v[168:169], v[176:177]
	v_pk_mul_f32 v[170:171], v[170:171], v[178:179]
	v_pk_mul_f32 v[172:173], v[172:173], v[180:181]
	v_pk_mul_f32 v[174:175], v[174:175], v[182:183]
	ds_write_b128 v184, v[168:171]
	ds_write_b128 v184, v[172:175] offset:16
	s_waitcnt vmcnt(12)
	v_lshlrev_b32_e32 v176, 16, v148
	v_and_b32_e32 v177, 0xffff0000, v148
	v_lshlrev_b32_e32 v178, 16, v149
	v_and_b32_e32 v179, 0xffff0000, v149
	v_lshlrev_b32_e32 v180, 16, v150
	v_and_b32_e32 v181, 0xffff0000, v150
	v_lshlrev_b32_e32 v182, 16, v151
	v_and_b32_e32 v183, 0xffff0000, v151
	v_rcp_f32_e32 v176, v176
	v_rcp_f32_e32 v177, v177
	v_rcp_f32_e32 v178, v178
	v_rcp_f32_e32 v179, v179
	v_rcp_f32_e32 v180, v180
	v_rcp_f32_e32 v181, v181
	v_rcp_f32_e32 v182, v182
	v_rcp_f32_e32 v183, v183
	v_lshlrev_b32_e32 v168, 16, v144
	v_and_b32_e32 v169, 0xffff0000, v144
	v_lshlrev_b32_e32 v170, 16, v145
	v_and_b32_e32 v171, 0xffff0000, v145
	v_lshlrev_b32_e32 v172, 16, v146
	v_and_b32_e32 v173, 0xffff0000, v146
	v_lshlrev_b32_e32 v174, 16, v147
	v_and_b32_e32 v175, 0xffff0000, v147
	v_pk_mul_f32 v[168:169], v[168:169], v[176:177]
	v_pk_mul_f32 v[170:171], v[170:171], v[178:179]
	v_pk_mul_f32 v[172:173], v[172:173], v[180:181]
	v_pk_mul_f32 v[174:175], v[174:175], v[182:183]
	ds_write_b128 v184, v[168:171] offset:16640
	ds_write_b128 v184, v[172:175] offset:16656
	s_waitcnt vmcnt(10)
; __device__ __forceinline__ float bflo(unsigned v) { return __uint_as_float(v << 16); }
; __device__ __forceinline__ float bfhi(unsigned v) { return __uint_as_float(v & 0xffff0000u); }
; __device__ __forceinline__ void phase4(const Params& p, char* shm) {
;     ...
;         for (int i = 0; i < 8; ++i) { const int id = tid + (b8 * 8 + i) * NTHR, row = id >> 6, c = id & 63;
;           f32x4 rt = { bflo(ga[i][0]) * __builtin_amdgcn_rcpf(bflo(gb[i][0])), bfhi(ga[i][0]) * __builtin_amdgcn_rcpf(bfhi(gb[i][0])),
;                        bflo(ga[i][1]) * __builtin_amdgcn_rcpf(bflo(gb[i][1])), bfhi(ga[i][1]) * __builtin_amdgcn_rcpf(bfhi(gb[i][1])) };
;           *reinterpret_cast<f32x4*>(shm + (row * CF_LD + c * 4) * 4) = rt; }
	v_lshlrev_b32_e32 v176, 16, v156
	v_and_b32_e32 v177, 0xffff0000, v156
	v_lshlrev_b32_e32 v178, 16, v157
	v_and_b32_e32 v179, 0xffff0000, v157
	v_lshlrev_b32_e32 v180, 16, v158
	v_and_b32_e32 v181, 0xffff0000, v158
	v_lshlrev_b32_e32 v182, 16, v159
	v_and_b32_e32 v183, 0xffff0000, v159
	v_rcp_f32_e32 v176, v176
	v_rcp_f32_e32 v177, v177
	v_rcp_f32_e32 v178, v178
	v_rcp_f32_e32 v179, v179
	v_rcp_f32_e32 v180, v180
	v_rcp_f32_e32 v181, v181
	v_rcp_f32_e32 v182, v182
	v_rcp_f32_e32 v183, v183
	v_lshlrev_b32_e32 v168, 16, v152
	v_and_b32_e32 v169, 0xffff0000, v152
	v_lshlrev_b32_e32 v170, 16, v153
	v_and_b32_e32 v171, 0xffff0000, v153
	v_lshlrev_b32_e32 v172, 16, v154
	v_and_b32_e32 v173, 0xffff0000, v154
	v_lshlrev_b32_e32 v174, 16, v155
	v_and_b32_e32 v175, 0xffff0000, v155
	v_pk_mul_f32 v[168:169], v[168:169], v[176:177]
	v_pk_mul_f32 v[170:171], v[170:171], v[178:179]
	v_pk_mul_f32 v[172:173], v[172:173], v[180:181]
	v_pk_mul_f32 v[174:175], v[174:175], v[182:183]
	ds_write_b128 v184, v[168:171] offset:33280
	ds_write_b128 v184, v[172:175] offset:33296
	s_waitcnt vmcnt(8)
	v_lshlrev_b32_e32 v176, 16, v164
	v_and_b32_e32 v177, 0xffff0000, v164
	v_lshlrev_b32_e32 v178, 16, v165
	v_and_b32_e32 v179, 0xffff0000, v165
	v_lshlrev_b32_e32 v180, 16, v166
	v_and_b32_e32 v181, 0xffff0000, v166
	v_lshlrev_b32_e32 v182, 16, v167
	v_and_b32_e32 v183, 0xffff0000, v167
	v_rcp_f32_e32 v176, v176
	v_rcp_f32_e32 v177, v177
	v_rcp_f32_e32 v178, v178
	v_rcp_f32_e32 v179, v179
	v_rcp_f32_e32 v180, v180
	v_rcp_f32_e32 v181, v181
	v_rcp_f32_e32 v182, v182
	v_rcp_f32_e32 v183, v183
	v_lshlrev_b32_e32 v168, 16, v160
	v_and_b32_e32 v169, 0xffff0000, v160
	v_lshlrev_b32_e32 v170, 16, v161
	v_and_b32_e32 v171, 0xffff0000, v161
	v_lshlrev_b32_e32 v172, 16, v162
	v_and_b32_e32 v173, 0xffff0000, v162
	v_lshlrev_b32_e32 v174, 16, v163
	v_and_b32_e32 v175, 0xffff0000, v163
	v_pk_mul_f32 v[168:169], v[168:169], v[176:177]
	v_pk_mul_f32 v[170:171], v[170:171], v[178:179]
	v_pk_mul_f32 v[172:173], v[172:173], v[180:181]
	v_pk_mul_f32 v[174:175], v[174:175], v[182:183]
	ds_write_b128 v184, v[168:171] offset:49920
	ds_write_b128 v184, v[172:175] offset:49936
	s_waitcnt vmcnt(6)
	v_lshlrev_b32_e32 v176, 16, v192
	v_and_b32_e32 v177, 0xffff0000, v192
	v_lshlrev_b32_e32 v178, 16, v193
	v_and_b32_e32 v179, 0xffff0000, v193
	v_lshlrev_b32_e32 v180, 16, v194
	v_and_b32_e32 v181, 0xffff0000, v194
	v_lshlrev_b32_e32 v182, 16, v195
	v_and_b32_e32 v183, 0xffff0000, v195
	v_rcp_f32_e32 v176, v176
	v_rcp_f32_e32 v177, v177
	v_rcp_f32_e32 v178, v178
	v_rcp_f32_e32 v179, v179
	v_rcp_f32_e32 v180, v180
	v_rcp_f32_e32 v181, v181
	v_rcp_f32_e32 v182, v182
	v_rcp_f32_e32 v183, v183
	v_lshlrev_b32_e32 v168, 16, v188
	v_and_b32_e32 v169, 0xffff0000, v188
	v_lshlrev_b32_e32 v170, 16, v189
	v_and_b32_e32 v171, 0xffff0000, v189
	v_lshlrev_b32_e32 v172, 16, v190
	v_and_b32_e32 v173, 0xffff0000, v190
	v_lshlrev_b32_e32 v174, 16, v191
	v_and_b32_e32 v175, 0xffff0000, v191
	v_pk_mul_f32 v[168:169], v[168:169], v[176:177]
	v_pk_mul_f32 v[170:171], v[170:171], v[178:179]
	v_pk_mul_f32 v[172:173], v[172:173], v[180:181]
	v_pk_mul_f32 v[174:175], v[174:175], v[182:183]
	ds_write_b128 v185, v[168:171]
	ds_write_b128 v185, v[172:175] offset:16
	s_waitcnt vmcnt(4)
	v_lshlrev_b32_e32 v176, 16, v200
	v_and_b32_e32 v177, 0xffff0000, v200
	v_lshlrev_b32_e32 v178, 16, v201
	v_and_b32_e32 v179, 0xffff0000, v201
	v_lshlrev_b32_e32 v180, 16, v202
	v_and_b32_e32 v181, 0xffff0000, v202
	v_lshlrev_b32_e32 v182, 16, v203
	v_and_b32_e32 v183, 0xffff0000, v203
	v_rcp_f32_e32 v176, v176
	v_rcp_f32_e32 v177, v177
	v_rcp_f32_e32 v178, v178
	v_rcp_f32_e32 v179, v179
	v_rcp_f32_e32 v180, v180
	v_rcp_f32_e32 v181, v181
	v_rcp_f32_e32 v182, v182
	v_rcp_f32_e32 v183, v183
	v_lshlrev_b32_e32 v168, 16, v196
	v_and_b32_e32 v169, 0xffff0000, v196
	v_lshlrev_b32_e32 v170, 16, v197
	v_and_b32_e32 v171, 0xffff0000, v197
	v_lshlrev_b32_e32 v172, 16, v198
	v_and_b32_e32 v173, 0xffff0000, v198
	v_lshlrev_b32_e32 v174, 16, v199
	v_and_b32_e32 v175, 0xffff0000, v199
	v_pk_mul_f32 v[168:169], v[168:169], v[176:177]
	v_pk_mul_f32 v[170:171], v[170:171], v[178:179]
	v_pk_mul_f32 v[172:173], v[172:173], v[180:181]
	v_pk_mul_f32 v[174:175], v[174:175], v[182:183]
	ds_write_b128 v185, v[168:171] offset:16640
	ds_write_b128 v185, v[172:175] offset:16656
	s_waitcnt vmcnt(2)
	v_lshlrev_b32_e32 v176, 16, v208
	v_and_b32_e32 v177, 0xffff0000, v208
	v_lshlrev_b32_e32 v178, 16, v209
	v_and_b32_e32 v179, 0xffff0000, v209
	v_lshlrev_b32_e32 v180, 16, v210
	v_and_b32_e32 v181, 0xffff0000, v210
	v_lshlrev_b32_e32 v182, 16, v211
	v_and_b32_e32 v183, 0xffff0000, v211
	v_rcp_f32_e32 v176, v176
	v_rcp_f32_e32 v177, v177
	v_rcp_f32_e32 v178, v178
	v_rcp_f32_e32 v179, v179
	v_rcp_f32_e32 v180, v180
	v_rcp_f32_e32 v181, v181
	v_rcp_f32_e32 v182, v182
	v_rcp_f32_e32 v183, v183
	v_lshlrev_b32_e32 v168, 16, v204
	v_and_b32_e32 v169, 0xffff0000, v204
	v_lshlrev_b32_e32 v170, 16, v205
	v_and_b32_e32 v171, 0xffff0000, v205
	v_lshlrev_b32_e32 v172, 16, v206
	v_and_b32_e32 v173, 0xffff0000, v206
	v_lshlrev_b32_e32 v174, 16, v207
	v_and_b32_e32 v175, 0xffff0000, v207
	v_pk_mul_f32 v[168:169], v[168:169], v[176:177]
	v_pk_mul_f32 v[170:171], v[170:171], v[178:179]
	v_pk_mul_f32 v[172:173], v[172:173], v[180:181]
	v_pk_mul_f32 v[174:175], v[174:175], v[182:183]
	ds_write_b128 v185, v[168:171] offset:33280
	ds_write_b128 v185, v[172:175] offset:33296
	s_waitcnt vmcnt(0)
	v_lshlrev_b32_e32 v176, 16, v216
	v_and_b32_e32 v177, 0xffff0000, v216
	v_lshlrev_b32_e32 v178, 16, v217
	v_and_b32_e32 v179, 0xffff0000, v217
	v_lshlrev_b32_e32 v180, 16, v218
	v_and_b32_e32 v181, 0xffff0000, v218
	v_lshlrev_b32_e32 v182, 16, v219
	v_and_b32_e32 v183, 0xffff0000, v219
	v_rcp_f32_e32 v176, v176
	v_rcp_f32_e32 v177, v177
	v_rcp_f32_e32 v178, v178
	v_rcp_f32_e32 v179, v179
	v_rcp_f32_e32 v180, v180
	v_rcp_f32_e32 v181, v181
	v_rcp_f32_e32 v182, v182
	v_rcp_f32_e32 v183, v183
	v_lshlrev_b32_e32 v168, 16, v212
	v_and_b32_e32 v169, 0xffff0000, v212
	v_lshlrev_b32_e32 v170, 16, v213
	v_and_b32_e32 v171, 0xffff0000, v213
	v_lshlrev_b32_e32 v172, 16, v214
	v_and_b32_e32 v173, 0xffff0000, v214
	v_lshlrev_b32_e32 v174, 16, v215
	v_and_b32_e32 v175, 0xffff0000, v215
	v_pk_mul_f32 v[168:169], v[168:169], v[176:177]
	v_pk_mul_f32 v[170:171], v[170:171], v[178:179]
	v_pk_mul_f32 v[172:173], v[172:173], v[180:181]
	v_pk_mul_f32 v[174:175], v[174:175], v[182:183]
	ds_write_b128 v185, v[168:171] offset:49920
	ds_write_b128 v185, v[172:175] offset:49936
	s_waitcnt lgkmcnt(0)
	s_barrier
; __device__ __forceinline__ void phase4(const Params& p, char* shm) {
;     ...
; #pragma unroll
;       for (int bj = 0; bj < 2; ++bj)
; #pragma unroll
;         for (int m = 0; m < 4; ++m)
; #pragma unroll
;           for (int n = 0; n < 2; ++n) acc[ai][bj][m][n] *= *(const f32x4*)(cfb + CF_OFF(bj, m, n));
;       __syncthreads();
	ds_read_b128 v[168:171], v252
	ds_read_b128 v[172:175], v252 offset:64
	ds_read_b128 v[176:179], v252 offset:512
	ds_read_b128 v[180:183], v252 offset:576
	s_waitcnt lgkmcnt(3)
	v_pk_mul_f32 v[66:67], v[66:67], v[168:169]
	v_pk_mul_f32 v[68:69], v[68:69], v[170:171]
	s_waitcnt lgkmcnt(2)
	v_pk_mul_f32 v[62:63], v[62:63], v[172:173]
	v_pk_mul_f32 v[64:65], v[64:65], v[174:175]
	s_waitcnt lgkmcnt(1)
	v_pk_mul_f32 v[34:35], v[34:35], v[176:177]
	v_pk_mul_f32 v[36:37], v[36:37], v[178:179]
	s_waitcnt lgkmcnt(0)
	v_pk_mul_f32 v[30:31], v[30:31], v[180:181]
	v_pk_mul_f32 v[32:33], v[32:33], v[182:183]
	ds_read_b128 v[168:171], v252 offset:16640
	ds_read_b128 v[172:175], v252 offset:16704
	ds_read_b128 v[176:179], v252 offset:17152
	ds_read_b128 v[180:183], v252 offset:17216
	s_waitcnt lgkmcnt(3)
	v_pk_mul_f32 v[58:59], v[58:59], v[168:169]
	v_pk_mul_f32 v[60:61], v[60:61], v[170:171]
	s_waitcnt lgkmcnt(2)
	v_pk_mul_f32 v[54:55], v[54:55], v[172:173]
	v_pk_mul_f32 v[56:57], v[56:57], v[174:175]
	s_waitcnt lgkmcnt(1)
	v_pk_mul_f32 v[26:27], v[26:27], v[176:177]
	v_pk_mul_f32 v[28:29], v[28:29], v[178:179]
	s_waitcnt lgkmcnt(0)
	v_pk_mul_f32 v[22:23], v[22:23], v[180:181]
	v_pk_mul_f32 v[24:25], v[24:25], v[182:183]
	ds_read_b128 v[168:171], v252 offset:33280
	ds_read_b128 v[172:175], v252 offset:33344
	ds_read_b128 v[176:179], v252 offset:33792
	ds_read_b128 v[180:183], v252 offset:33856
	s_waitcnt lgkmcnt(3)
	v_pk_mul_f32 v[50:51], v[50:51], v[168:169]
	v_pk_mul_f32 v[52:53], v[52:53], v[170:171]
	s_waitcnt lgkmcnt(2)
	v_pk_mul_f32 v[46:47], v[46:47], v[172:173]
	v_pk_mul_f32 v[48:49], v[48:49], v[174:175]
	s_waitcnt lgkmcnt(1)
	v_pk_mul_f32 v[18:19], v[18:19], v[176:177]
	v_pk_mul_f32 v[20:21], v[20:21], v[178:179]
	s_waitcnt lgkmcnt(0)
	v_pk_mul_f32 v[14:15], v[14:15], v[180:181]
	v_pk_mul_f32 v[16:17], v[16:17], v[182:183]
	ds_read_b128 v[168:171], v252 offset:49920
	ds_read_b128 v[172:175], v252 offset:49984
	ds_read_b128 v[176:179], v252 offset:50432
	ds_read_b128 v[180:183], v252 offset:50496
	s_waitcnt lgkmcnt(3)
	v_pk_mul_f32 v[42:43], v[42:43], v[168:169]
	v_pk_mul_f32 v[44:45], v[44:45], v[170:171]
	s_waitcnt lgkmcnt(2)
	v_pk_mul_f32 v[38:39], v[38:39], v[172:173]
	v_pk_mul_f32 v[40:41], v[40:41], v[174:175]
	s_waitcnt lgkmcnt(1)
	v_pk_mul_f32 v[10:11], v[10:11], v[176:177]
	v_pk_mul_f32 v[12:13], v[12:13], v[178:179]
	s_waitcnt lgkmcnt(0)
	v_pk_mul_f32 v[6:7], v[6:7], v[180:181]
	v_pk_mul_f32 v[8:9], v[8:9], v[182:183]
	s_barrier
	s_branch .LBB0_450
